# EpiResid epilogue (ph3/8/11): residual loads of three row groups in flight with counted vmcnt instead of load-wait-store per 16 bytes
# speedup vs baseline: 1.0099x; 1.0099x over previous
; #define PG8_STAGE(bufoff, gbase, voff) do { _Pragma("unroll") for (int _i = 0; _i < 2; ++_i) \
;         __builtin_amdgcn_global_load_lds((const unsigned*)((const char*)(gbase) + (voff)[_i]), (LAS unsigned*)(lds + (bufoff) + ldsw + _i * 8192), 16, 0, 0); } while (0)
; #define PG8_LDA(dst, b, h) do { _Pragma("unroll") for (int m = 0; m < 4; ++m) _Pragma("unroll") for (int k = 0; k < 2; ++k) dst[m][k] = *(const LAS bf16x8*)(lds + PG8_SA(b, h) + aoff + m * 2048 + k * 1024); } while (0)
; #define PG8_LDB(dst, b, h) do { _Pragma("unroll") for (int n = 0; n < 2; ++n) _Pragma("unroll") for (int k = 0; k < 2; ++k) dst[n][k] = *(const LAS bf16x8*)(lds + PG8_SB(b, h) + boff + n * 2048 + k * 1024); } while (0)
; #define PG8_WAIT_V(n) asm volatile("s_waitcnt vmcnt(" #n ")" ::: "memory")
; #define PG8_WAIT_L(n) asm volatile("s_waitcnt lgkmcnt(" #n ")" ::: "memory")
; #define PG8_BAR __builtin_amdgcn_s_barrier()
; #define PG8_SCHED __builtin_amdgcn_sched_barrier(0)
; template <class Epi>
; __device__ __forceinline__ void gemm_phase(LAS unsigned char* lds, const Gemm g, const StaticOrder& S, const Epi& E) {
;     ...
;         for (int t = 0; t < nt; t += 2) {
;             const bool last = (t == nt - 2);
;             const char* a1 = cA + (size_t)(t + 1) * kstep;
;             const char* a2 = last ? nA : cA + (size_t)(t + 2) * kstep; const char* b2 = last ? nB : cB + (size_t)(t + 2) * kstep;
;             const char* a3 = a2 + kstep; const char* b3 = b2 + kstep;
;             PG8_LDB(B0, 0, 0); PG8_SCHED; PG8_LDA(At, 0, 0); PG8_STAGE(PG8_SA(1, 1), a1 + hstep, voffA);
;             PG8_WAIT_L(8); PG8_BAR; PG8_WAIT_L(0); PG8_MMA(0, 0, At, B0); PG8_BAR; PG8_SCHED;
;             PG8_LDB(B1, 0, 1); PG8_STAGE(PG8_SB(0, 0), b2, voffB);
;             PG8_BAR; PG8_WAIT_L(0); PG8_MMA(0, 1, At, B1); PG8_BAR;
;             PG8_LDA(At, 0, 1); PG8_STAGE(PG8_SA(0, 0), a2, voffA);
;             PG8_BAR; PG8_WAIT_L(0); PG8_MMA(1, 0, At, B0); PG8_BAR; PG8_SCHED;
;             PG8_STAGE(PG8_SB(0, 1), b2 + hstep, voffB);
;             PG8_WAIT_V(6); PG8_BAR; PG8_MMA(1, 1, At, B1); PG8_BAR;
;             PG8_LDB(B0, 1, 0); PG8_SCHED; PG8_LDA(At, 1, 0); PG8_STAGE(PG8_SA(0, 1), a2 + hstep, voffA);
;             PG8_WAIT_L(8); PG8_BAR; PG8_WAIT_L(0); PG8_MMA(0, 0, At, B0); PG8_BAR; PG8_SCHED;
.LBB0_1151:
	s_add_i32 s46, s22, 2
	s_add_u32 s24, s20, 0x80
	s_addc_u32 s23, s21, 0
	s_add_i32 s47, 0, 0x10000
	v_add_u32_e32 v135, s47, v164
	ds_read_b128 v[142:145], v135
	ds_read_b128 v[146:149], v135 offset:1024
	ds_read_b128 v[150:153], v135 offset:2048
	ds_read_b128 v[154:157], v135 offset:3072
	s_cmp_eq_u32 s57, s22
	s_cselect_b32 s22, s16, s24
	s_cselect_b32 s23, s17, s23
	s_cselect_b32 s25, s19, s45
	s_cselect_b32 s24, s18, s44
	v_lshl_add_u64 v[162:163], s[20:21], 0, v[138:139]
	s_add_i32 m0, s40, 0xc000
	ds_read_b128 v[158:161], v166
	ds_read_b128 v[168:171], v166 offset:1024
	ds_read_b128 v[172:175], v166 offset:2048
	ds_read_b128 v[186:189], v166 offset:3072
	ds_read_b128 v[210:213], v166 offset:4096
	ds_read_b128 v[214:217], v166 offset:5120
	ds_read_b128 v[218:221], v166 offset:6144
	ds_read_b128 v[222:225], v166 offset:7168
	global_load_lds_dwordx4 v[162:163], off
	v_lshl_add_u64 v[162:163], s[20:21], 0, v[140:141]
	s_add_i32 m0, s40, 0xe000
	s_nop 0
	global_load_lds_dwordx4 v[162:163], off
	s_waitcnt lgkmcnt(8)
	s_barrier
	s_waitcnt lgkmcnt(0)
	s_setprio 1
	s_waitcnt lgkmcnt(0)
	v_mfma_f32_16x16x32_bf16 v[126:129], v[142:145], v[158:161], v[126:129]
	v_mfma_f32_16x16x32_bf16 v[122:125], v[150:153], v[158:161], v[122:125]
	v_mfma_f32_16x16x32_bf16 v[110:113], v[142:145], v[172:175], v[110:113]
	v_mfma_f32_16x16x32_bf16 v[106:109], v[150:153], v[172:175], v[106:109]
	v_mfma_f32_16x16x32_bf16 v[92:95], v[142:145], v[210:213], v[92:95]
	v_mfma_f32_16x16x32_bf16 v[88:91], v[150:153], v[210:213], v[88:91]
	v_mfma_f32_16x16x32_bf16 v[76:79], v[142:145], v[218:221], v[76:79]
	v_mfma_f32_16x16x32_bf16 v[72:75], v[150:153], v[218:221], v[72:75]
	v_mfma_f32_16x16x32_bf16 v[126:129], v[146:149], v[168:171], v[126:129]
	v_mfma_f32_16x16x32_bf16 v[122:125], v[154:157], v[168:171], v[122:125]
	v_mfma_f32_16x16x32_bf16 v[110:113], v[146:149], v[186:189], v[110:113]
	v_mfma_f32_16x16x32_bf16 v[106:109], v[154:157], v[186:189], v[106:109]
	v_mfma_f32_16x16x32_bf16 v[92:95], v[146:149], v[214:217], v[92:95]
	v_mfma_f32_16x16x32_bf16 v[88:91], v[154:157], v[214:217], v[88:91]
	v_mfma_f32_16x16x32_bf16 v[76:79], v[146:149], v[222:225], v[76:79]
	v_mfma_f32_16x16x32_bf16 v[72:75], v[154:157], v[222:225], v[72:75]
	s_setprio 0
	s_barrier
	s_add_i32 s67, 0, 0x14000
	s_add_i32 s47, s47, s31
	v_add_u32_e32 v135, s67, v164
	v_lshl_add_u64 v[162:163], s[24:25], 0, v[132:133]
	s_mov_b32 m0, s47
	ds_read_b128 v[226:229], v135
	ds_read_b128 v[230:233], v135 offset:1024
	ds_read_b128 v[234:237], v135 offset:2048
	ds_read_b128 v[238:241], v135 offset:3072
	global_load_lds_dwordx4 v[162:163], off
	v_lshl_add_u64 v[176:177], s[24:25], 0, v[130:131]
	s_add_i32 m0, s47, 0x2000
	s_nop 0
	global_load_lds_dwordx4 v[176:177], off
	s_barrier
	s_waitcnt lgkmcnt(0)
	s_setprio 1
	s_waitcnt lgkmcnt(0)
	v_mfma_f32_16x16x32_bf16 v[118:121], v[226:229], v[158:161], v[118:121]
	v_mfma_f32_16x16x32_bf16 v[114:117], v[234:237], v[158:161], v[114:117]
	v_mfma_f32_16x16x32_bf16 v[102:105], v[226:229], v[172:175], v[102:105]
	v_mfma_f32_16x16x32_bf16 v[98:101], v[234:237], v[172:175], v[98:101]
	v_mfma_f32_16x16x32_bf16 v[84:87], v[226:229], v[210:213], v[84:87]
	v_mfma_f32_16x16x32_bf16 v[80:83], v[234:237], v[210:213], v[80:83]
	v_mfma_f32_16x16x32_bf16 v[68:71], v[226:229], v[218:221], v[68:71]
	v_mfma_f32_16x16x32_bf16 v[64:67], v[234:237], v[218:221], v[64:67]
	v_mfma_f32_16x16x32_bf16 v[118:121], v[230:233], v[168:171], v[118:121]
	v_mfma_f32_16x16x32_bf16 v[114:117], v[238:241], v[168:171], v[114:117]
	v_mfma_f32_16x16x32_bf16 v[102:105], v[230:233], v[186:189], v[102:105]
	v_mfma_f32_16x16x32_bf16 v[98:101], v[238:241], v[186:189], v[98:101]
	v_mfma_f32_16x16x32_bf16 v[84:87], v[230:233], v[214:217], v[84:87]
	v_mfma_f32_16x16x32_bf16 v[80:83], v[238:241], v[214:217], v[80:83]
	v_mfma_f32_16x16x32_bf16 v[68:71], v[230:233], v[222:225], v[68:71]
	v_mfma_f32_16x16x32_bf16 v[64:67], v[238:241], v[222:225], v[64:67]
	s_setprio 0
	s_mov_b32 m0, s40
	v_lshl_add_u64 v[198:199], s[22:23], 0, v[132:133]
	s_barrier
	ds_read_b128 v[158:161], v166 offset:16384
	ds_read_b128 v[168:171], v166 offset:17408
	ds_read_b128 v[172:175], v166 offset:18432
	ds_read_b128 v[186:189], v166 offset:19456
	ds_read_b128 v[210:213], v166 offset:20480
	ds_read_b128 v[214:217], v166 offset:21504
	ds_read_b128 v[218:221], v166 offset:22528
	ds_read_b128 v[222:225], v166 offset:23552
	global_load_lds_dwordx4 v[198:199], off
	v_lshl_add_u64 v[200:201], s[22:23], 0, v[130:131]
	s_mov_b32 m0, s41
	s_nop 0
	global_load_lds_dwordx4 v[200:201], off
	s_barrier
	s_waitcnt lgkmcnt(0)
	s_setprio 1
	s_waitcnt lgkmcnt(0)
	v_mfma_f32_16x16x32_bf16 v[60:63], v[142:145], v[158:161], v[60:63]
	v_mfma_f32_16x16x32_bf16 v[56:59], v[150:153], v[158:161], v[56:59]
	v_mfma_f32_16x16x32_bf16 v[44:47], v[142:145], v[172:175], v[44:47]
	v_mfma_f32_16x16x32_bf16 v[40:43], v[150:153], v[172:175], v[40:43]
	v_mfma_f32_16x16x32_bf16 v[28:31], v[142:145], v[210:213], v[28:31]
	v_mfma_f32_16x16x32_bf16 v[24:27], v[150:153], v[210:213], v[24:27]
	v_mfma_f32_16x16x32_bf16 v[12:15], v[142:145], v[218:221], v[12:15]
	v_mfma_f32_16x16x32_bf16 v[8:11], v[150:153], v[218:221], v[8:11]
	v_mfma_f32_16x16x32_bf16 v[60:63], v[146:149], v[168:171], v[60:63]
	v_mfma_f32_16x16x32_bf16 v[56:59], v[154:157], v[168:171], v[56:59]
	v_mfma_f32_16x16x32_bf16 v[44:47], v[146:149], v[186:189], v[44:47]
	v_mfma_f32_16x16x32_bf16 v[40:43], v[154:157], v[186:189], v[40:43]
	v_mfma_f32_16x16x32_bf16 v[28:31], v[146:149], v[214:217], v[28:31]
	v_mfma_f32_16x16x32_bf16 v[24:27], v[154:157], v[214:217], v[24:27]
	v_mfma_f32_16x16x32_bf16 v[12:15], v[146:149], v[222:225], v[12:15]
	v_mfma_f32_16x16x32_bf16 v[8:11], v[154:157], v[222:225], v[8:11]
	s_setprio 0
	s_barrier
; #define PG8_STAGE(bufoff, gbase, voff) do { _Pragma("unroll") for (int _i = 0; _i < 2; ++_i) \
;         __builtin_amdgcn_global_load_lds((const unsigned*)((const char*)(gbase) + (voff)[_i]), (LAS unsigned*)(lds + (bufoff) + ldsw + _i * 8192), 16, 0, 0); } while (0)
; #define PG8_LDA(dst, b, h) do { _Pragma("unroll") for (int m = 0; m < 4; ++m) _Pragma("unroll") for (int k = 0; k < 2; ++k) dst[m][k] = *(const LAS bf16x8*)(lds + PG8_SA(b, h) + aoff + m * 2048 + k * 1024); } while (0)
; #define PG8_LDB(dst, b, h) do { _Pragma("unroll") for (int n = 0; n < 2; ++n) _Pragma("unroll") for (int k = 0; k < 2; ++k) dst[n][k] = *(const LAS bf16x8*)(lds + PG8_SB(b, h) + boff + n * 2048 + k * 1024); } while (0)
; #define PG8_MMA(ai, bj, At, Bt) do { __builtin_amdgcn_s_setprio(1); _Pragma("unroll") for (int m = 0; m < 4; ++m) _Pragma("unroll") for (int n = 0; n < 2; ++n) _Pragma("unroll") for (int k = 0; k < 2; ++k) \
;         acc[ai][bj][m][n] = __builtin_amdgcn_mfma_f32_16x16x32_bf16(Bt[n][k], At[m][k], acc[ai][bj][m][n], 0, 0, 0); __builtin_amdgcn_s_setprio(0); } while (0)
; #define PG8_WAIT_V(n) asm volatile("s_waitcnt vmcnt(" #n ")" ::: "memory")
; #define PG8_WAIT_L(n) asm volatile("s_waitcnt lgkmcnt(" #n ")" ::: "memory")
; #define PG8_BAR __builtin_amdgcn_s_barrier()
; #define PG8_SCHED __builtin_amdgcn_sched_barrier(0)
; template <class Epi>
; __device__ __forceinline__ void gemm_phase(LAS unsigned char* lds, const Gemm g, const StaticOrder& S, const Epi& E) {
;     ...
;             PG8_WAIT_V(6); PG8_BAR; PG8_MMA(1, 1, At, B1); PG8_BAR;
;             PG8_LDB(B0, 1, 0); PG8_SCHED; PG8_LDA(At, 1, 0); PG8_STAGE(PG8_SA(0, 1), a2 + hstep, voffA);
;             PG8_WAIT_L(8); PG8_BAR; PG8_WAIT_L(0); PG8_MMA(0, 0, At, B0); PG8_BAR; PG8_SCHED;
;             PG8_LDB(B1, 1, 1); PG8_STAGE(PG8_SB(1, 0), b3, voffB);
;             PG8_BAR; PG8_WAIT_L(0); PG8_MMA(0, 1, At, B1); PG8_BAR;
;             PG8_LDA(At, 1, 1); PG8_STAGE(PG8_SA(1, 0), a3, voffA);
;             PG8_BAR; PG8_WAIT_L(0); PG8_MMA(1, 0, At, B0); PG8_BAR; PG8_SCHED;
	s_add_u32 s24, s24, s14
	s_addc_u32 s25, s25, 0
	s_add_i32 s47, s67, s31
	v_lshl_add_u64 v[242:243], s[24:25], 0, v[132:133]
	s_mov_b32 m0, s47
	v_lshl_add_u64 v[244:245], s[24:25], 0, v[130:131]
	global_load_lds_dwordx4 v[242:243], off
	s_add_i32 m0, s47, 0x2000
	s_nop 0
	global_load_lds_dwordx4 v[244:245], off
	s_waitcnt vmcnt(6)
	s_barrier
	s_setprio 1
	v_mfma_f32_16x16x32_bf16 v[52:55], v[226:229], v[158:161], v[52:55]
	v_mfma_f32_16x16x32_bf16 v[48:51], v[234:237], v[158:161], v[48:51]
	v_mfma_f32_16x16x32_bf16 v[36:39], v[226:229], v[172:175], v[36:39]
	v_mfma_f32_16x16x32_bf16 v[32:35], v[234:237], v[172:175], v[32:35]
	v_mfma_f32_16x16x32_bf16 v[20:23], v[226:229], v[210:213], v[20:23]
	v_mfma_f32_16x16x32_bf16 v[16:19], v[234:237], v[210:213], v[16:19]
	v_mfma_f32_16x16x32_bf16 v[4:7], v[226:229], v[218:221], v[4:7]
	v_mfma_f32_16x16x32_bf16 v[0:3], v[234:237], v[218:221], v[0:3]
	v_mfma_f32_16x16x32_bf16 v[52:55], v[230:233], v[168:171], v[52:55]
	v_mfma_f32_16x16x32_bf16 v[48:51], v[238:241], v[168:171], v[48:51]
	v_mfma_f32_16x16x32_bf16 v[36:39], v[230:233], v[186:189], v[36:39]
	v_mfma_f32_16x16x32_bf16 v[32:35], v[238:241], v[186:189], v[32:35]
	v_mfma_f32_16x16x32_bf16 v[20:23], v[230:233], v[214:217], v[20:23]
	v_mfma_f32_16x16x32_bf16 v[16:19], v[238:241], v[214:217], v[16:19]
	v_mfma_f32_16x16x32_bf16 v[4:7], v[230:233], v[222:225], v[4:7]
	v_mfma_f32_16x16x32_bf16 v[0:3], v[238:241], v[222:225], v[0:3]
	s_setprio 0
	s_add_i32 s24, 0, 0x18000
	v_add_u32_e32 v135, s24, v164
	s_barrier
	ds_read_b128 v[142:145], v135
	ds_read_b128 v[146:149], v135 offset:1024
	ds_read_b128 v[150:153], v135 offset:2048
	ds_read_b128 v[154:157], v135 offset:3072
	s_add_u32 s22, s22, s14
	s_addc_u32 s23, s23, 0
	s_mov_b32 m0, s48
	v_lshl_add_u64 v[226:227], s[22:23], 0, v[132:133]
	ds_read_b128 v[158:161], v166 offset:32768
	ds_read_b128 v[168:171], v166 offset:33792
	ds_read_b128 v[172:175], v166 offset:34816
	ds_read_b128 v[186:189], v166 offset:35840
	ds_read_b128 v[210:213], v166 offset:36864
	ds_read_b128 v[214:217], v166 offset:37888
	ds_read_b128 v[218:221], v166 offset:38912
	ds_read_b128 v[222:225], v166 offset:39936
	global_load_lds_dwordx4 v[226:227], off
	v_lshl_add_u64 v[226:227], s[22:23], 0, v[130:131]
	s_mov_b32 m0, s49
	s_nop 0
	global_load_lds_dwordx4 v[226:227], off
	s_waitcnt lgkmcnt(8)
	s_barrier
	s_waitcnt lgkmcnt(0)
	s_setprio 1
	s_waitcnt lgkmcnt(0)
	v_mfma_f32_16x16x32_bf16 v[126:129], v[142:145], v[158:161], v[126:129]
	v_mfma_f32_16x16x32_bf16 v[122:125], v[150:153], v[158:161], v[122:125]
	v_mfma_f32_16x16x32_bf16 v[110:113], v[142:145], v[172:175], v[110:113]
	v_mfma_f32_16x16x32_bf16 v[106:109], v[150:153], v[172:175], v[106:109]
	v_mfma_f32_16x16x32_bf16 v[92:95], v[142:145], v[210:213], v[92:95]
	v_mfma_f32_16x16x32_bf16 v[88:91], v[150:153], v[210:213], v[88:91]
	v_mfma_f32_16x16x32_bf16 v[76:79], v[142:145], v[218:221], v[76:79]
	v_mfma_f32_16x16x32_bf16 v[72:75], v[150:153], v[218:221], v[72:75]
	v_mfma_f32_16x16x32_bf16 v[126:129], v[146:149], v[168:171], v[126:129]
	v_mfma_f32_16x16x32_bf16 v[122:125], v[154:157], v[168:171], v[122:125]
	v_mfma_f32_16x16x32_bf16 v[110:113], v[146:149], v[186:189], v[110:113]
	v_mfma_f32_16x16x32_bf16 v[106:109], v[154:157], v[186:189], v[106:109]
	v_mfma_f32_16x16x32_bf16 v[92:95], v[146:149], v[214:217], v[92:95]
	v_mfma_f32_16x16x32_bf16 v[88:91], v[154:157], v[214:217], v[88:91]
	v_mfma_f32_16x16x32_bf16 v[76:79], v[146:149], v[222:225], v[76:79]
	v_mfma_f32_16x16x32_bf16 v[72:75], v[154:157], v[222:225], v[72:75]
	s_setprio 0
	s_barrier
	s_add_i32 s22, 0, 0x1c000
	s_add_i32 s23, s24, s31
	v_add_u32_e32 v135, s22, v164
	v_lshl_add_u64 v[162:163], v[162:163], 0, s[86:87]
	s_mov_b32 m0, s23
	ds_read_b128 v[226:229], v135
	ds_read_b128 v[230:233], v135 offset:1024
	ds_read_b128 v[234:237], v135 offset:2048
	ds_read_b128 v[238:241], v135 offset:3072
	global_load_lds_dwordx4 v[162:163], off
	v_lshl_add_u64 v[162:163], v[176:177], 0, s[86:87]
	s_add_i32 m0, s23, 0x2000
	s_nop 0
	global_load_lds_dwordx4 v[162:163], off
	s_barrier
	s_waitcnt lgkmcnt(0)
	s_setprio 1
	s_waitcnt lgkmcnt(0)
	v_mfma_f32_16x16x32_bf16 v[118:121], v[226:229], v[158:161], v[118:121]
	v_mfma_f32_16x16x32_bf16 v[114:117], v[234:237], v[158:161], v[114:117]
	v_mfma_f32_16x16x32_bf16 v[102:105], v[226:229], v[172:175], v[102:105]
	v_mfma_f32_16x16x32_bf16 v[98:101], v[234:237], v[172:175], v[98:101]
	v_mfma_f32_16x16x32_bf16 v[84:87], v[226:229], v[210:213], v[84:87]
	v_mfma_f32_16x16x32_bf16 v[80:83], v[234:237], v[210:213], v[80:83]
	v_mfma_f32_16x16x32_bf16 v[68:71], v[226:229], v[218:221], v[68:71]
	v_mfma_f32_16x16x32_bf16 v[64:67], v[234:237], v[218:221], v[64:67]
	v_mfma_f32_16x16x32_bf16 v[118:121], v[230:233], v[168:171], v[118:121]
	v_mfma_f32_16x16x32_bf16 v[114:117], v[238:241], v[168:171], v[114:117]
	v_mfma_f32_16x16x32_bf16 v[102:105], v[230:233], v[186:189], v[102:105]
	v_mfma_f32_16x16x32_bf16 v[98:101], v[238:241], v[186:189], v[98:101]
	v_mfma_f32_16x16x32_bf16 v[84:87], v[230:233], v[214:217], v[84:87]
	v_mfma_f32_16x16x32_bf16 v[80:83], v[238:241], v[214:217], v[80:83]
	v_mfma_f32_16x16x32_bf16 v[68:71], v[230:233], v[222:225], v[68:71]
	v_mfma_f32_16x16x32_bf16 v[64:67], v[238:241], v[222:225], v[64:67]
	s_setprio 0
	s_mov_b32 m0, s53
	v_lshl_add_u64 v[162:163], v[198:199], 0, s[86:87]
	s_barrier
	ds_read_b128 v[158:161], v166 offset:49152
	ds_read_b128 v[168:171], v166 offset:50176
	ds_read_b128 v[172:175], v166 offset:51200
	ds_read_b128 v[186:189], v166 offset:52224
	ds_read_b128 v[210:213], v166 offset:53248
	ds_read_b128 v[214:217], v166 offset:54272
	ds_read_b128 v[218:221], v166 offset:55296
	ds_read_b128 v[222:225], v166 offset:56320
	global_load_lds_dwordx4 v[162:163], off
	v_lshl_add_u64 v[162:163], v[200:201], 0, s[86:87]
	s_mov_b32 m0, s54
	s_nop 0
	global_load_lds_dwordx4 v[162:163], off
	s_barrier
; #define PG8_STAGE(bufoff, gbase, voff) do { _Pragma("unroll") for (int _i = 0; _i < 2; ++_i) \
;         __builtin_amdgcn_global_load_lds((const unsigned*)((const char*)(gbase) + (voff)[_i]), (LAS unsigned*)(lds + (bufoff) + ldsw + _i * 8192), 16, 0, 0); } while (0)
; #define PG8_MMA(ai, bj, At, Bt) do { __builtin_amdgcn_s_setprio(1); _Pragma("unroll") for (int m = 0; m < 4; ++m) _Pragma("unroll") for (int n = 0; n < 2; ++n) _Pragma("unroll") for (int k = 0; k < 2; ++k) \
;         acc[ai][bj][m][n] = __builtin_amdgcn_mfma_f32_16x16x32_bf16(Bt[n][k], At[m][k], acc[ai][bj][m][n], 0, 0, 0); __builtin_amdgcn_s_setprio(0); } while (0)
; #define PG8_WAIT_V(n) asm volatile("s_waitcnt vmcnt(" #n ")" ::: "memory")
; #define PG8_WAIT_L(n) asm volatile("s_waitcnt lgkmcnt(" #n ")" ::: "memory")
; #define PG8_BAR __builtin_amdgcn_s_barrier()
; template <class Epi>
; __device__ __forceinline__ void gemm_phase(LAS unsigned char* lds, const Gemm g, const StaticOrder& S, const Epi& E) {
;     ...
;             PG8_BAR; PG8_WAIT_L(0); PG8_MMA(1, 0, At, B0); PG8_BAR; PG8_SCHED;
;             PG8_STAGE(PG8_SB(1, 1), b3 + hstep, voffB);
;             PG8_WAIT_V(6); PG8_BAR; PG8_MMA(1, 1, At, B1); PG8_BAR;
;     __device__ __forceinline__ void operator()(const f32x4 (&acc)[2][2][4][2], const pg8::Unit& u, int wr, int wc, int fr, int fq) const {
;         const bool isctx = u.pm >= 64; const int b = isctx ? 8 : (u.pm >> 3);
;         const int row0 = (isctx ? (u.pm - 64) : u.pm) * 256 + wr * 64 + fr, col0 = u.pn * 256 + wc * 32 + 4 * fq;
;         const float* gp = mod + (size_t)(b * NMOD + gidx) * DM + col0;
;         const float* rb = isctx ? resid_c : resid_l; float* ob = isctx ? out_c : out_l;
;         f32x4 gv[2][2];
; #pragma unroll
;         for (int bj = 0; bj < 2; ++bj)
; #pragma unroll
;             for (int n = 0; n < 2; ++n) gv[bj][n] = *(const f32x4*)(gp + bj * 128 + n * 16) * coef;
; #pragma unroll
;         for (int ai = 0; ai < 2; ++ai)
; #pragma unroll
;             for (int m = 0; m < 4; ++m) {
;                 const size_t o = (size_t)(row0 + ai * 128 + m * 16) * DM + col0;
; #pragma unroll
;                 for (int bj = 0; bj < 2; ++bj)
; #pragma unroll
;                     for (int n = 0; n < 2; ++n) { const f32x4 r = *(const f32x4*)(rb + o + bj * 128 + n * 16); *(f32x4*)(ob + o + bj * 128 + n * 16) = r + gv[bj][n] * acc[ai][bj][m][n]; }
	s_waitcnt lgkmcnt(0)
	s_setprio 1
	s_waitcnt lgkmcnt(0)
	v_mfma_f32_16x16x32_bf16 v[60:63], v[142:145], v[158:161], v[60:63]
	v_mfma_f32_16x16x32_bf16 v[56:59], v[150:153], v[158:161], v[56:59]
	v_mfma_f32_16x16x32_bf16 v[44:47], v[142:145], v[172:175], v[44:47]
	v_mfma_f32_16x16x32_bf16 v[40:43], v[150:153], v[172:175], v[40:43]
	v_mfma_f32_16x16x32_bf16 v[28:31], v[142:145], v[210:213], v[28:31]
	v_mfma_f32_16x16x32_bf16 v[24:27], v[150:153], v[210:213], v[24:27]
	v_mfma_f32_16x16x32_bf16 v[12:15], v[142:145], v[218:221], v[12:15]
	v_mfma_f32_16x16x32_bf16 v[8:11], v[150:153], v[218:221], v[8:11]
	v_mfma_f32_16x16x32_bf16 v[60:63], v[146:149], v[168:171], v[60:63]
	v_mfma_f32_16x16x32_bf16 v[56:59], v[154:157], v[168:171], v[56:59]
	v_mfma_f32_16x16x32_bf16 v[44:47], v[146:149], v[186:189], v[44:47]
	v_mfma_f32_16x16x32_bf16 v[40:43], v[154:157], v[186:189], v[40:43]
	v_mfma_f32_16x16x32_bf16 v[28:31], v[146:149], v[214:217], v[28:31]
	v_mfma_f32_16x16x32_bf16 v[24:27], v[154:157], v[214:217], v[24:27]
	v_mfma_f32_16x16x32_bf16 v[12:15], v[146:149], v[222:225], v[12:15]
	v_mfma_f32_16x16x32_bf16 v[8:11], v[154:157], v[222:225], v[8:11]
	s_setprio 0
	s_barrier
	s_add_i32 s22, s22, s31
	v_lshl_add_u64 v[142:143], v[242:243], 0, s[86:87]
	s_mov_b32 m0, s22
	s_nop 0
	global_load_lds_dwordx4 v[142:143], off
	v_lshl_add_u64 v[142:143], v[244:245], 0, s[86:87]
	s_add_i32 m0, s22, 0x2000
	s_nop 0
	global_load_lds_dwordx4 v[142:143], off
	s_waitcnt vmcnt(6)
	s_barrier
	s_setprio 1
	v_mfma_f32_16x16x32_bf16 v[52:55], v[226:229], v[158:161], v[52:55]
	v_mfma_f32_16x16x32_bf16 v[48:51], v[234:237], v[158:161], v[48:51]
	v_mfma_f32_16x16x32_bf16 v[36:39], v[226:229], v[172:175], v[36:39]
	v_mfma_f32_16x16x32_bf16 v[32:35], v[234:237], v[172:175], v[32:35]
	v_mfma_f32_16x16x32_bf16 v[20:23], v[226:229], v[210:213], v[20:23]
	v_mfma_f32_16x16x32_bf16 v[16:19], v[234:237], v[210:213], v[16:19]
	v_mfma_f32_16x16x32_bf16 v[4:7], v[226:229], v[218:221], v[4:7]
	v_mfma_f32_16x16x32_bf16 v[0:3], v[234:237], v[218:221], v[0:3]
	v_mfma_f32_16x16x32_bf16 v[52:55], v[230:233], v[168:171], v[52:55]
	v_mfma_f32_16x16x32_bf16 v[48:51], v[238:241], v[168:171], v[48:51]
	v_mfma_f32_16x16x32_bf16 v[36:39], v[230:233], v[186:189], v[36:39]
	v_mfma_f32_16x16x32_bf16 v[32:35], v[238:241], v[186:189], v[32:35]
	v_mfma_f32_16x16x32_bf16 v[20:23], v[230:233], v[214:217], v[20:23]
	v_mfma_f32_16x16x32_bf16 v[16:19], v[238:241], v[214:217], v[16:19]
	v_mfma_f32_16x16x32_bf16 v[4:7], v[230:233], v[222:225], v[4:7]
	v_mfma_f32_16x16x32_bf16 v[0:3], v[238:241], v[222:225], v[0:3]
	s_setprio 0
	s_add_u32 s20, s20, 0x100
	s_addc_u32 s21, s21, 0
	s_add_u32 s44, s44, 0x100
	s_addc_u32 s45, s45, 0
	s_cmp_ge_u32 s46, s55
	s_mov_b32 s22, s46
	s_barrier
	s_cbranch_scc0 .LBB0_1151
	s_lshl_b32 s21, s61, 8
	s_ashr_i32 s20, s61, 3
	s_add_i32 s22, s21, 0xffffc000
	v_readlane_b32 s68, v254, 60
	s_cmp_gt_i32 s61, 63
	s_mul_i32 s20, s20, 9
	v_readlane_b32 s80, v255, 8
	v_readlane_b32 s81, v255, 9
	v_readlane_b32 s82, v255, 10
	v_readlane_b32 s83, v255, 11
	s_cselect_b32 s24, 0x48, s20
	v_readlane_b32 s72, v255, 0
	v_readlane_b32 s73, v255, 1
	s_mov_b64 s[80:81], s[88:89]
	s_cselect_b32 s44, s22, s21
	s_cselect_b32 s21, s73, s50
	s_cselect_b32 s20, s72, s51
	s_cselect_b32 s23, 0, s81
	s_cselect_b32 s22, 0, s80
	s_add_i32 s24, s24, s52
	s_ashr_i32 s25, s24, 31
	s_mov_b64 s[82:83], s[90:91]
	s_lshl_b64 s[24:25], s[24:25], 13
	v_lshl_or_b32 v160, s66, 8, v165
	s_add_u32 s24, s82, s24
	s_addc_u32 s25, s83, s25
	v_ashrrev_i32_e32 v161, 31, v160
	v_lshl_add_u64 v[158:159], v[160:161], 2, s[24:25]
	global_load_dwordx4 v[142:145], v[158:159], off
	global_load_dwordx4 v[146:149], v[158:159], off offset:64
	global_load_dwordx4 v[150:153], v[158:159], off offset:512
	global_load_dwordx4 v[154:157], v[158:159], off offset:576
	v_mov_b32_e32 v135, v134
	v_add_u32_e32 v162, s44, v97
	v_lshlrev_b32_e32 v163, 11, v162
	v_add_u32_e32 v163, v163, v160
	v_lshlrev_b32_e32 v163, 2, v163
	global_load_dwordx4 v[210:213], v163, s[20:21]
	global_load_dwordx4 v[214:217], v163, s[20:21] offset:64
	global_load_dwordx4 v[218:221], v163, s[20:21] offset:512
	global_load_dwordx4 v[222:225], v163, s[20:21] offset:576
	s_add_u32 s20, s20, 0x20000
	s_addc_u32 s21, s21, 0
	global_load_dwordx4 v[226:229], v163, s[20:21]
	global_load_dwordx4 v[230:233], v163, s[20:21] offset:64
	global_load_dwordx4 v[234:237], v163, s[20:21] offset:512
	global_load_dwordx4 v[238:241], v163, s[20:21] offset:576
	s_add_u32 s20, s20, 0x20000
	s_addc_u32 s21, s21, 0
	global_load_dwordx4 v[168:171], v163, s[20:21]
	global_load_dwordx4 v[172:175], v163, s[20:21] offset:64
	global_load_dwordx4 v[186:189], v163, s[20:21] offset:512
	global_load_dwordx4 v[198:201], v163, s[20:21] offset:576
	s_add_u32 s20, s20, 0x20000
	s_addc_u32 s21, s21, 0
	s_and_b64 vcc, exec, s[42:43]
	s_mov_b32 s66, s59
	s_mov_b32 s61, s58
	v_readlane_b32 s69, v254, 61
	v_readlane_b32 s70, v254, 62
	v_readlane_b32 s71, v254, 63
	v_readlane_b32 s74, v255, 2
	v_readlane_b32 s75, v255, 3
	v_readlane_b32 s76, v255, 4
	v_readlane_b32 s77, v255, 5
	v_readlane_b32 s78, v255, 6
	v_readlane_b32 s79, v255, 7
	s_waitcnt vmcnt(12)
	v_pk_mul_f32 v[142:143], v[136:137], v[142:143]
	v_pk_mul_f32 v[144:145], v[134:135], v[144:145]
	v_pk_mul_f32 v[146:147], v[136:137], v[146:147]
	v_pk_mul_f32 v[148:149], v[134:135], v[148:149]
	v_pk_mul_f32 v[150:151], v[136:137], v[150:151]
	v_pk_mul_f32 v[152:153], v[134:135], v[152:153]
	v_pk_mul_f32 v[154:155], v[136:137], v[154:155]
	v_pk_mul_f32 v[156:157], v[134:135], v[156:157]
	s_waitcnt vmcnt(8)
;     __device__ __forceinline__ void operator()(const f32x4 (&acc)[2][2][4][2], const pg8::Unit& u, int wr, int wc, int fr, int fq) const {
;     ...
; #pragma unroll
;         for (int ai = 0; ai < 2; ++ai)
; #pragma unroll
;             for (int m = 0; m < 4; ++m) {
;                 const size_t o = (size_t)(row0 + ai * 128 + m * 16) * DM + col0;
; #pragma unroll
;                 for (int bj = 0; bj < 2; ++bj)
; #pragma unroll
;                     for (int n = 0; n < 2; ++n) { const f32x4 r = *(const f32x4*)(rb + o + bj * 128 + n * 16); *(f32x4*)(ob + o + bj * 128 + n * 16) = r + gv[bj][n] * acc[ai][bj][m][n]; }
	v_pk_fma_f32 v[128:129], v[128:129], v[144:145], v[212:213]
	v_pk_fma_f32 v[126:127], v[126:127], v[142:143], v[210:211]
	v_pk_fma_f32 v[124:125], v[124:125], v[148:149], v[216:217]
	v_pk_fma_f32 v[122:123], v[122:123], v[146:147], v[214:215]
	v_pk_fma_f32 v[120:121], v[120:121], v[152:153], v[220:221]
	v_pk_fma_f32 v[118:119], v[118:119], v[150:151], v[218:219]
	v_pk_fma_f32 v[116:117], v[116:117], v[156:157], v[224:225]
	v_pk_fma_f32 v[114:115], v[114:115], v[154:155], v[222:223]
	global_store_dwordx4 v163, v[126:129], s[22:23]
	global_store_dwordx4 v163, v[122:125], s[22:23] offset:64
	global_store_dwordx4 v163, v[118:121], s[22:23] offset:512
	global_store_dwordx4 v163, v[114:117], s[22:23] offset:576
	s_add_u32 s22, s22, 0x20000
	s_addc_u32 s23, s23, 0
	global_load_dwordx4 v[210:213], v163, s[20:21]
	global_load_dwordx4 v[214:217], v163, s[20:21] offset:64
	global_load_dwordx4 v[218:221], v163, s[20:21] offset:512
	global_load_dwordx4 v[222:225], v163, s[20:21] offset:576
	s_add_u32 s20, s20, 0xa0000
	s_addc_u32 s21, s21, 0
	s_waitcnt vmcnt(12)
	v_pk_fma_f32 v[112:113], v[112:113], v[144:145], v[228:229]
	v_pk_fma_f32 v[110:111], v[110:111], v[142:143], v[226:227]
	v_pk_fma_f32 v[108:109], v[108:109], v[148:149], v[232:233]
	v_pk_fma_f32 v[106:107], v[106:107], v[146:147], v[230:231]
	v_pk_fma_f32 v[104:105], v[104:105], v[152:153], v[236:237]
	v_pk_fma_f32 v[102:103], v[102:103], v[150:151], v[234:235]
	v_pk_fma_f32 v[100:101], v[100:101], v[156:157], v[240:241]
	v_pk_fma_f32 v[98:99], v[98:99], v[154:155], v[238:239]
	global_store_dwordx4 v163, v[110:113], s[22:23]
	global_store_dwordx4 v163, v[106:109], s[22:23] offset:64
	global_store_dwordx4 v163, v[102:105], s[22:23] offset:512
	global_store_dwordx4 v163, v[98:101], s[22:23] offset:576
	s_add_u32 s22, s22, 0x20000
	s_addc_u32 s23, s23, 0
	global_load_dwordx4 v[226:229], v163, s[20:21]
	global_load_dwordx4 v[230:233], v163, s[20:21] offset:64
	global_load_dwordx4 v[234:237], v163, s[20:21] offset:512
	global_load_dwordx4 v[238:241], v163, s[20:21] offset:576
	s_add_u32 s20, s20, 0x20000
	s_addc_u32 s21, s21, 0
	s_waitcnt vmcnt(16)
	v_pk_fma_f32 v[94:95], v[94:95], v[144:145], v[170:171]
	v_pk_fma_f32 v[92:93], v[92:93], v[142:143], v[168:169]
	v_pk_fma_f32 v[90:91], v[90:91], v[148:149], v[174:175]
	v_pk_fma_f32 v[88:89], v[88:89], v[146:147], v[172:173]
	v_pk_fma_f32 v[86:87], v[86:87], v[152:153], v[188:189]
	v_pk_fma_f32 v[84:85], v[84:85], v[150:151], v[186:187]
	v_pk_fma_f32 v[82:83], v[82:83], v[156:157], v[200:201]
	v_pk_fma_f32 v[80:81], v[80:81], v[154:155], v[198:199]
	global_store_dwordx4 v163, v[92:95], s[22:23]
	global_store_dwordx4 v163, v[88:91], s[22:23] offset:64
	global_store_dwordx4 v163, v[84:87], s[22:23] offset:512
	global_store_dwordx4 v163, v[80:83], s[22:23] offset:576
	s_add_u32 s22, s22, 0x20000
	s_addc_u32 s23, s23, 0
	global_load_dwordx4 v[168:171], v163, s[20:21]
	global_load_dwordx4 v[172:175], v163, s[20:21] offset:64
	global_load_dwordx4 v[186:189], v163, s[20:21] offset:512
	global_load_dwordx4 v[198:201], v163, s[20:21] offset:576
	s_add_u32 s20, s20, 0x20000
	s_addc_u32 s21, s21, 0
	s_waitcnt vmcnt(16)
	v_pk_fma_f32 v[78:79], v[78:79], v[144:145], v[212:213]
	v_pk_fma_f32 v[76:77], v[76:77], v[142:143], v[210:211]
	v_pk_fma_f32 v[74:75], v[74:75], v[148:149], v[216:217]
	v_pk_fma_f32 v[72:73], v[72:73], v[146:147], v[214:215]
	v_pk_fma_f32 v[70:71], v[70:71], v[152:153], v[220:221]
	v_pk_fma_f32 v[68:69], v[68:69], v[150:151], v[218:219]
	v_pk_fma_f32 v[66:67], v[66:67], v[156:157], v[224:225]
	v_pk_fma_f32 v[64:65], v[64:65], v[154:155], v[222:223]
	global_store_dwordx4 v163, v[76:79], s[22:23]
	global_store_dwordx4 v163, v[72:75], s[22:23] offset:64
	global_store_dwordx4 v163, v[68:71], s[22:23] offset:512
	global_store_dwordx4 v163, v[64:67], s[22:23] offset:576
	s_add_u32 s22, s22, 0xa0000
	s_addc_u32 s23, s23, 0
	global_load_dwordx4 v[210:213], v163, s[20:21]
	global_load_dwordx4 v[214:217], v163, s[20:21] offset:64
	global_load_dwordx4 v[218:221], v163, s[20:21] offset:512
	global_load_dwordx4 v[222:225], v163, s[20:21] offset:576
	s_add_u32 s20, s20, 0x20000
	s_addc_u32 s21, s21, 0
	s_waitcnt vmcnt(16)
;     __device__ __forceinline__ void operator()(const f32x4 (&acc)[2][2][4][2], const pg8::Unit& u, int wr, int wc, int fr, int fq) const {
;     ...
; #pragma unroll
;         for (int ai = 0; ai < 2; ++ai)
; #pragma unroll
;             for (int m = 0; m < 4; ++m) {
;                 const size_t o = (size_t)(row0 + ai * 128 + m * 16) * DM + col0;
; #pragma unroll
;                 for (int bj = 0; bj < 2; ++bj)
; #pragma unroll
;                     for (int n = 0; n < 2; ++n) { const f32x4 r = *(const f32x4*)(rb + o + bj * 128 + n * 16); *(f32x4*)(ob + o + bj * 128 + n * 16) = r + gv[bj][n] * acc[ai][bj][m][n]; }
	v_pk_fma_f32 v[62:63], v[62:63], v[144:145], v[228:229]
	v_pk_fma_f32 v[60:61], v[60:61], v[142:143], v[226:227]
	v_pk_fma_f32 v[58:59], v[58:59], v[148:149], v[232:233]
	v_pk_fma_f32 v[56:57], v[56:57], v[146:147], v[230:231]
	v_pk_fma_f32 v[54:55], v[54:55], v[152:153], v[236:237]
	v_pk_fma_f32 v[52:53], v[52:53], v[150:151], v[234:235]
	v_pk_fma_f32 v[50:51], v[50:51], v[156:157], v[240:241]
	v_pk_fma_f32 v[48:49], v[48:49], v[154:155], v[238:239]
	global_store_dwordx4 v163, v[60:63], s[22:23]
	global_store_dwordx4 v163, v[56:59], s[22:23] offset:64
	global_store_dwordx4 v163, v[52:55], s[22:23] offset:512
	global_store_dwordx4 v163, v[48:51], s[22:23] offset:576
	s_add_u32 s22, s22, 0x20000
	s_addc_u32 s23, s23, 0
	global_load_dwordx4 v[226:229], v163, s[20:21]
	global_load_dwordx4 v[230:233], v163, s[20:21] offset:64
	global_load_dwordx4 v[234:237], v163, s[20:21] offset:512
	global_load_dwordx4 v[238:241], v163, s[20:21] offset:576
	s_add_u32 s20, s20, 0x20000
	s_addc_u32 s21, s21, 0
	s_waitcnt vmcnt(16)
	v_pk_fma_f32 v[46:47], v[46:47], v[144:145], v[170:171]
	v_pk_fma_f32 v[44:45], v[44:45], v[142:143], v[168:169]
	v_pk_fma_f32 v[42:43], v[42:43], v[148:149], v[174:175]
	v_pk_fma_f32 v[40:41], v[40:41], v[146:147], v[172:173]
	v_pk_fma_f32 v[38:39], v[38:39], v[152:153], v[188:189]
	v_pk_fma_f32 v[36:37], v[36:37], v[150:151], v[186:187]
	v_pk_fma_f32 v[34:35], v[34:35], v[156:157], v[200:201]
	v_pk_fma_f32 v[32:33], v[32:33], v[154:155], v[198:199]
	global_store_dwordx4 v163, v[44:47], s[22:23]
	global_store_dwordx4 v163, v[40:43], s[22:23] offset:64
	global_store_dwordx4 v163, v[36:39], s[22:23] offset:512
	global_store_dwordx4 v163, v[32:35], s[22:23] offset:576
	s_add_u32 s22, s22, 0x20000
	s_addc_u32 s23, s23, 0
	s_waitcnt vmcnt(12)
	v_pk_fma_f32 v[30:31], v[30:31], v[144:145], v[212:213]
	v_pk_fma_f32 v[28:29], v[28:29], v[142:143], v[210:211]
	v_pk_fma_f32 v[26:27], v[26:27], v[148:149], v[216:217]
	v_pk_fma_f32 v[24:25], v[24:25], v[146:147], v[214:215]
	v_pk_fma_f32 v[22:23], v[22:23], v[152:153], v[220:221]
	v_pk_fma_f32 v[20:21], v[20:21], v[150:151], v[218:219]
	v_pk_fma_f32 v[18:19], v[18:19], v[156:157], v[224:225]
	v_pk_fma_f32 v[16:17], v[16:17], v[154:155], v[222:223]
	global_store_dwordx4 v163, v[28:31], s[22:23]
	global_store_dwordx4 v163, v[24:27], s[22:23] offset:64
	global_store_dwordx4 v163, v[20:23], s[22:23] offset:512
	global_store_dwordx4 v163, v[16:19], s[22:23] offset:576
	s_add_u32 s22, s22, 0x20000
	s_addc_u32 s23, s23, 0
	s_waitcnt vmcnt(8)
	v_pk_fma_f32 v[14:15], v[14:15], v[144:145], v[228:229]
	v_pk_fma_f32 v[12:13], v[12:13], v[142:143], v[226:227]
	v_pk_fma_f32 v[10:11], v[10:11], v[148:149], v[232:233]
	v_pk_fma_f32 v[8:9], v[8:9], v[146:147], v[230:231]
	v_pk_fma_f32 v[6:7], v[6:7], v[152:153], v[236:237]
	v_pk_fma_f32 v[4:5], v[4:5], v[150:151], v[234:235]
	v_pk_fma_f32 v[2:3], v[2:3], v[156:157], v[240:241]
	v_pk_fma_f32 v[0:1], v[0:1], v[154:155], v[238:239]
	global_store_dwordx4 v163, v[12:15], s[22:23]
	global_store_dwordx4 v163, v[8:11], s[22:23] offset:64
	global_store_dwordx4 v163, v[4:7], s[22:23] offset:512
	global_store_dwordx4 v163, v[0:3], s[22:23] offset:576
	s_mov_b64 s[22:23], s[18:19]
	s_mov_b64 s[20:21], s[16:17]
	s_cbranch_vccz .LBB0_1140
	s_waitcnt vmcnt(0)
	s_cmpk_gt_u32 s30, 0xff
	s_cbranch_scc1 .LBB0_1155
	s_barrier
